# v18 with the attention tile loops shifted by 40 bytes (placement only)
# baseline (speedup 1.0000x reference)
.LBB0_270:
	s_waitcnt lgkmcnt(0)
	v_max_f32_e32 v1, v1, v1
	v_max_f32_e32 v0, v0, v0
	v_max_f32_e32 v69, v0, v1
	v_sub_f32_e32 v32, v32, v69
	v_sub_f32_e32 v16, v16, v69
	v_sub_f32_e32 v33, v33, v69
	v_sub_f32_e32 v68, v46, v69
	v_sub_f32_e32 v46, v17, v69
	v_exp_f32_e32 v16, v16
	v_exp_f32_e32 v17, v32
	v_sub_f32_e32 v34, v34, v69
	v_sub_f32_e32 v70, v47, v69
	v_sub_f32_e32 v47, v18, v69
	v_sub_f32_e32 v71, v19, v69
	v_exp_f32_e32 v18, v46
	v_exp_f32_e32 v19, v33
	v_sub_f32_e32 v35, v35, v69
	v_sub_f32_e32 v72, v20, v69
	v_sub_f32_e32 v73, v21, v69
	v_exp_f32_e32 v20, v47
	v_exp_f32_e32 v21, v34
	v_sub_f32_e32 v36, v36, v69
	v_sub_f32_e32 v74, v22, v69
	v_sub_f32_e32 v75, v23, v69
	v_exp_f32_e32 v22, v71
	v_exp_f32_e32 v23, v35
	v_sub_f32_e32 v37, v37, v69
	v_sub_f32_e32 v76, v24, v69
	v_sub_f32_e32 v77, v25, v69
	v_sub_f32_e32 v78, v26, v69
	v_sub_f32_e32 v79, v27, v69
	v_pk_add_f32 v[24:25], v[16:17], 0 op_sel_hi:[1,0]
	v_exp_f32_e32 v26, v72
	v_exp_f32_e32 v27, v36
	v_sub_f32_e32 v38, v38, v69
	v_sub_f32_e32 v80, v28, v69
	v_sub_f32_e32 v81, v29, v69
	v_pk_add_f32 v[24:25], v[18:19], v[24:25]
	v_exp_f32_e32 v28, v73
	v_exp_f32_e32 v29, v37
	v_sub_f32_e32 v39, v39, v69
	v_sub_f32_e32 v82, v30, v69
	v_sub_f32_e32 v83, v31, v69
	v_pk_add_f32 v[24:25], v[20:21], v[24:25]
	v_exp_f32_e32 v30, v74
	v_exp_f32_e32 v31, v38
	v_sub_f32_e32 v40, v40, v69
	v_pk_add_f32 v[24:25], v[22:23], v[24:25]
	v_exp_f32_e32 v32, v75
	v_exp_f32_e32 v33, v39
	v_sub_f32_e32 v41, v41, v69
	v_exp_f32_e32 v34, v76
	v_exp_f32_e32 v35, v40
	v_pk_add_f32 v[24:25], v[26:27], v[24:25]
	v_sub_f32_e32 v42, v42, v69
	v_exp_f32_e32 v36, v77
	v_exp_f32_e32 v37, v41
	v_pk_add_f32 v[24:25], v[28:29], v[24:25]
	v_sub_f32_e32 v43, v43, v69
	v_exp_f32_e32 v38, v78
	v_exp_f32_e32 v39, v42
	v_pk_add_f32 v[24:25], v[30:31], v[24:25]
	v_sub_f32_e32 v44, v44, v69
	v_exp_f32_e32 v40, v79
	v_exp_f32_e32 v41, v43
	v_pk_add_f32 v[24:25], v[32:33], v[24:25]
	v_sub_f32_e32 v45, v45, v69
	v_exp_f32_e32 v42, v80
	v_exp_f32_e32 v43, v44
	v_pk_add_f32 v[24:25], v[34:35], v[24:25]
	v_exp_f32_e32 v44, v81
	v_exp_f32_e32 v45, v45
	v_pk_add_f32 v[24:25], v[36:37], v[24:25]
	v_exp_f32_e32 v46, v82
	v_exp_f32_e32 v47, v68
	v_pk_add_f32 v[24:25], v[38:39], v[24:25]
	v_exp_f32_e32 v82, v83
	v_exp_f32_e32 v83, v70
	v_pk_add_f32 v[24:25], v[40:41], v[24:25]
	s_add_i32 s64, s64, 1
	v_exp_f32_e64 v0, -v69
	v_pk_add_f32 v[24:25], v[42:43], v[24:25]
	s_cmp_lt_u32 s64, s37
	v_pk_add_f32 v[24:25], v[44:45], v[24:25]
	s_cselect_b32 s12, s96, 0
	v_pk_add_f32 v[24:25], v[46:47], v[24:25]
	s_add_i32 s27, s12, s27
	v_pk_add_f32 v[24:25], v[82:83], v[24:25]
	s_ashr_i32 s12, s27, 6
	s_bfe_u32 s54, s27, 0x20004
	v_mul_f32_e32 v0, 0, v0
	v_pk_add_f32 v[24:25], v[24:25], v[24:25] op_sel:[0,1] op_sel_hi:[1,0]
	s_lshl_b32 s36, s12, 4
	s_lshl_b32 s53, s54, 1
	v_mov_b32_e32 v68, v0
	v_mov_b32_e32 v25, v189
	s_or_b32 s53, s53, s36
	s_lshl_b32 s36, s63, 7
	s_and_b32 s55, s58, 0x780
	v_pk_add_f32 v[206:207], v[68:69], v[24:25]
	v_cvt_pk_bf16_f32 v68, v16, v18
	s_and_b32 s36, s36, 0x1800
	v_add_lshl_u32 v16, v158, s55, 2
	v_sub_u32_e32 v16, s36, v16
	v_cvt_pk_bf16_f32 v69, v20, v22
	v_cvt_pk_bf16_f32 v70, v26, v28
	v_cvt_pk_bf16_f32 v71, v30, v32
	v_cvt_pk_bf16_f32 v76, v17, v19
	v_cvt_pk_bf16_f32 v77, v21, v23
	v_cvt_pk_bf16_f32 v78, v27, v29
	v_cvt_pk_bf16_f32 v79, v31, v33
	v_add_u32_e32 v167, v215, v16
	ds_read_b128 v[16:19], v64 offset:20480
	ds_read_b128 v[20:23], v65 offset:20480
	ds_read_b128 v[24:27], v66 offset:20480
	ds_read_b128 v[28:31], v67 offset:20480
	s_lshl_b32 s54, s54, 7
	s_lshl_b32 s12, s12, 9
	v_mov_b32_e32 v1, v0
	v_mov_b32_e32 v2, v0
	v_mov_b32_e32 v3, v0
	v_mov_b32_e32 v4, v0
	v_mov_b32_e32 v5, v0
	v_mov_b32_e32 v6, v0
	v_mov_b32_e32 v7, v0
	v_mov_b32_e32 v8, v0
	v_mov_b32_e32 v9, v0
	v_mov_b32_e32 v10, v0
	v_mov_b32_e32 v11, v0
	v_mov_b32_e32 v12, v0
	v_mov_b32_e32 v13, v0
	v_mov_b32_e32 v14, v0
	v_mov_b32_e32 v15, v0
	s_mov_b32 s23, 0
	s_sub_i32 s36, s62, s55
	s_or_b32 s12, s54, s12
	v_cvt_pk_bf16_f32 v72, v34, v36
	v_cvt_pk_bf16_f32 v73, v38, v40
	v_cvt_pk_bf16_f32 v74, v42, v44
	v_cvt_pk_bf16_f32 v75, v46, v82
	v_cvt_pk_bf16_f32 v80, v35, v37
	v_cvt_pk_bf16_f32 v81, v39, v41
	v_cvt_pk_bf16_f32 v82, v43, v45
	v_cvt_pk_bf16_f32 v83, v47, v83
	v_mfma_f32_32x32x16_bf16 v[32:47], v[56:59], v[68:71], v[0:15]
	v_mfma_f32_32x32x16_bf16 v[32:47], v[48:51], v[72:75], v[32:47]
	v_mfma_f32_32x32x16_bf16 v[32:47], v[60:63], v[76:79], v[32:47]
	v_mfma_f32_32x32x16_bf16 v[32:47], v[52:55], v[80:83], v[32:47]
	s_add_i32 s54, s33, 0x8000
	s_and_b32 s54, s54, 0x18000
	v_add_u32_e32 v48, s54, v149
	v_add_u32_e32 v49, v48, v157
	ds_read_b128 v[132:135], v49
	ds_read_b128 v[116:119], v49 offset:4096
	v_add_u32_e32 v49, v48, v193
	ds_read_b128 v[136:139], v49
	ds_read_b128 v[120:123], v49 offset:4096
	v_add_u32_e32 v49, v48, v208
	v_add_u32_e32 v48, v48, v209
	ds_read_b128 v[140:143], v49
	ds_read_b128 v[124:127], v49 offset:4096
	ds_read_b128 v[128:131], v48
	ds_read_b128 v[112:115], v48 offset:4096
	ds_read_b128 v[84:87], v64 offset:24576
	ds_read_b128 v[88:91], v65 offset:24576
	ds_read_b128 v[92:95], v66 offset:24576
	ds_read_b128 v[216:219], v67 offset:24576
	s_waitcnt lgkmcnt(0)
	v_mfma_f32_32x32x16_bf16 v[48:63], v[16:19], v[68:71], v[0:15]
	v_mfma_f32_32x32x16_bf16 v[48:63], v[20:23], v[72:75], v[48:63]
	v_mfma_f32_32x32x16_bf16 v[48:63], v[24:27], v[76:79], v[48:63]
	v_mfma_f32_32x32x16_bf16 v[48:63], v[28:31], v[80:83], v[48:63]
	ds_read_b128 v[220:223], v64 offset:28672
	ds_read_b128 v[234:237], v65 offset:28672
	ds_read_b128 v[238:241], v66 offset:28672
	ds_read_b128 v[64:67], v67 offset:28672
	v_mfma_f32_32x32x16_bf16 v[16:31], v[84:87], v[68:71], v[0:15]
	v_mfma_f32_32x32x16_bf16 v[16:31], v[88:91], v[72:75], v[16:31]
	v_mfma_f32_32x32x16_bf16 v[16:31], v[92:95], v[76:79], v[16:31]
	v_mfma_f32_32x32x16_bf16 v[16:31], v[216:219], v[80:83], v[16:31]
	s_waitcnt lgkmcnt(0)
	v_mfma_f32_32x32x16_bf16 v[0:15], v[220:223], v[68:71], v[0:15]
	s_waitcnt lgkmcnt(0)
	s_barrier
	s_add_i32 s65, s33, 0x10000
	s_mov_b32 s33, 0
	v_mfma_f32_32x32x16_bf16 v[0:15], v[234:237], v[72:75], v[0:15]
	v_mfma_f32_32x32x16_bf16 v[0:15], v[238:241], v[76:79], v[0:15]
	v_mfma_f32_32x32x16_bf16 v[0:15], v[64:67], v[80:83], v[0:15]
	s_setprio 0
	s_nop 0
	s_nop 0
	s_nop 0
	s_nop 0
	s_nop 0
	s_nop 0
	s_nop 0
	s_nop 0
	s_nop 0
	s_nop 0
	s_and_b64 vcc, exec, s[42:43]
	s_cbranch_vccnz .LqT_top

.LqT_rescale:
	s_mov_b32 s98, 0
	ds_bpermute_b32 v129, v210, v128
	s_waitcnt lgkmcnt(0)
	v_max_f32_e32 v129, v129, v129
	v_max_f32_e32 v128, v128, v129
	v_cmp_lt_f32_e32 vcc, s88, v128
	s_nop 0
	s_nop 0
	v_cndmask_b32_e32 v128, 0, v128, vcc
	v_exp_f32_e64 v130, -v128
	v_pk_add_f32 v[64:65], v[64:65], v[128:129] op_sel_hi:[1,0] neg_lo:[0,1] neg_hi:[0,1]
	v_pk_add_f32 v[80:81], v[80:81], v[128:129] op_sel_hi:[1,0] neg_lo:[0,1] neg_hi:[0,1]
	v_pk_add_f32 v[66:67], v[66:67], v[128:129] op_sel_hi:[1,0] neg_lo:[0,1] neg_hi:[0,1]
	v_pk_mul_f32 v[46:47], v[46:47], v[130:131] op_sel_hi:[1,0]
	v_pk_mul_f32 v[44:45], v[44:45], v[130:131] op_sel_hi:[1,0]
	v_pk_mul_f32 v[42:43], v[42:43], v[130:131] op_sel_hi:[1,0]
	v_pk_mul_f32 v[40:41], v[40:41], v[130:131] op_sel_hi:[1,0]
	v_pk_mul_f32 v[38:39], v[38:39], v[130:131] op_sel_hi:[1,0]
	v_pk_mul_f32 v[36:37], v[36:37], v[130:131] op_sel_hi:[1,0]
	v_pk_mul_f32 v[34:35], v[34:35], v[130:131] op_sel_hi:[1,0]
	v_pk_mul_f32 v[32:33], v[32:33], v[130:131] op_sel_hi:[1,0]
	v_pk_mul_f32 v[62:63], v[62:63], v[130:131] op_sel_hi:[1,0]
	v_pk_mul_f32 v[60:61], v[60:61], v[130:131] op_sel_hi:[1,0]
	v_pk_mul_f32 v[58:59], v[58:59], v[130:131] op_sel_hi:[1,0]
	v_pk_mul_f32 v[56:57], v[56:57], v[130:131] op_sel_hi:[1,0]
	v_pk_mul_f32 v[54:55], v[54:55], v[130:131] op_sel_hi:[1,0]
	v_pk_mul_f32 v[52:53], v[52:53], v[130:131] op_sel_hi:[1,0]
	v_pk_mul_f32 v[50:51], v[50:51], v[130:131] op_sel_hi:[1,0]
	v_pk_mul_f32 v[48:49], v[48:49], v[130:131] op_sel_hi:[1,0]
	v_pk_mul_f32 v[30:31], v[30:31], v[130:131] op_sel_hi:[1,0]
	v_pk_mul_f32 v[28:29], v[28:29], v[130:131] op_sel_hi:[1,0]
	v_pk_mul_f32 v[26:27], v[26:27], v[130:131] op_sel_hi:[1,0]
	v_pk_mul_f32 v[24:25], v[24:25], v[130:131] op_sel_hi:[1,0]
	v_pk_mul_f32 v[22:23], v[22:23], v[130:131] op_sel_hi:[1,0]
	v_pk_mul_f32 v[20:21], v[20:21], v[130:131] op_sel_hi:[1,0]
	v_pk_mul_f32 v[18:19], v[18:19], v[130:131] op_sel_hi:[1,0]
	v_pk_mul_f32 v[16:17], v[16:17], v[130:131] op_sel_hi:[1,0]
	v_pk_mul_f32 v[14:15], v[14:15], v[130:131] op_sel_hi:[1,0]
	v_pk_mul_f32 v[12:13], v[12:13], v[130:131] op_sel_hi:[1,0]
	v_pk_mul_f32 v[10:11], v[10:11], v[130:131] op_sel_hi:[1,0]
	v_pk_mul_f32 v[8:9], v[8:9], v[130:131] op_sel_hi:[1,0]
	v_pk_mul_f32 v[6:7], v[6:7], v[130:131] op_sel_hi:[1,0]
	v_pk_mul_f32 v[4:5], v[4:5], v[130:131] op_sel_hi:[1,0]
	v_pk_mul_f32 v[2:3], v[2:3], v[130:131] op_sel_hi:[1,0]
	v_pk_mul_f32 v[0:1], v[0:1], v[130:131] op_sel_hi:[1,0]
	v_mov_b32_e32 v131, v128
	v_pk_add_f32 v[82:83], v[82:83], v[128:129] op_sel_hi:[1,0] neg_lo:[0,1] neg_hi:[0,1]
	v_pk_add_f32 v[68:69], v[68:69], v[128:129] op_sel_hi:[1,0] neg_lo:[0,1] neg_hi:[0,1]
	v_pk_add_f32 v[84:85], v[84:85], v[128:129] op_sel_hi:[1,0] neg_lo:[0,1] neg_hi:[0,1]
	v_pk_add_f32 v[70:71], v[70:71], v[128:129] op_sel_hi:[1,0] neg_lo:[0,1] neg_hi:[0,1]
	v_pk_add_f32 v[86:87], v[86:87], v[128:129] op_sel_hi:[1,0] neg_lo:[0,1] neg_hi:[0,1]
	v_pk_add_f32 v[72:73], v[72:73], v[128:129] op_sel_hi:[1,0] neg_lo:[0,1] neg_hi:[0,1]
	v_pk_add_f32 v[88:89], v[88:89], v[128:129] op_sel_hi:[1,0] neg_lo:[0,1] neg_hi:[0,1]
	v_pk_add_f32 v[74:75], v[74:75], v[128:129] op_sel_hi:[1,0] neg_lo:[0,1] neg_hi:[0,1]
	v_pk_add_f32 v[90:91], v[90:91], v[128:129] op_sel_hi:[1,0] neg_lo:[0,1] neg_hi:[0,1]
	v_pk_add_f32 v[76:77], v[76:77], v[128:129] op_sel_hi:[1,0] neg_lo:[0,1] neg_hi:[0,1]
	v_pk_add_f32 v[92:93], v[92:93], v[128:129] op_sel_hi:[1,0] neg_lo:[0,1] neg_hi:[0,1]
	v_pk_add_f32 v[78:79], v[78:79], v[128:129] op_sel_hi:[1,0] neg_lo:[0,1] neg_hi:[0,1]
	v_pk_add_f32 v[94:95], v[94:95], v[128:129] op_sel_hi:[1,0] neg_lo:[0,1] neg_hi:[0,1]
	v_pk_add_f32 v[128:129], v[206:207], v[130:131]
	v_pk_mul_f32 v[206:207], v[206:207], v[130:131]
	s_nop 0
	v_mov_b32_e32 v207, v129
	s_branch .LqT_g0
	s_nop 0
	s_nop 0
	s_nop 0
	s_nop 0
	s_nop 0
	s_nop 0
	s_nop 0
	s_nop 0
